# PLE: second K-tile A rows requested at tile start, A-row loads cover whole 128-byte lines (two 8-byte LDS writes per quad), no store-drain wait at tile start
# baseline (speedup 1.0000x reference)
; DI unsigned pk2(float lo, float hi) { f32x2 v = {lo, hi}; return __builtin_bit_cast(unsigned, __builtin_convertvector(v, bf16x2_t)); }
; template <bool AF32, int AMODE, bool SWAP>
; DI void mainloop_rs(f32x16 (&acc)[2][2], const void* Abase, int lda, int arow0, int amax, const bf16_t* Bbase, int ldb, int brow0, int nk, int tid) {
;     ...
;     for (int i = 0; i < 4; ++i) { int row = arow0 + lr + 64 * i; row = row < 0 ? 0 : (row > amax ? amax : row); arow[i] = (long)row * lda + lc * 8; }
;     const bf16_t* bp = Bbase + (long)(brow0 + lr) * ldb + lc * 8;
;     auto gload = [&](int kt) {
;         const int ka = (AMODE == 1) ? ((kt >> 1) * 192 + (kt & 1) * 64) : kt * 64;
; #pragma unroll
;         for (int i = 0; i < 4; ++i) {
;             if (!AF32) ra.v[i] = *(const u32x4*)((const bf16_t*)Abase + arow[i] + ka);
;             else { const float* p = (const float*)Abase + arow[i] + ka; ra.v[2 * i] = *(const u32x4*)p; ra.v[2 * i + 1] = *(const u32x4*)(p + 4); }
;         }
; #pragma unroll
;         for (int i = 0; i < 2; ++i) rb[i] = *(const u32x4*)(bp + (long)(64 * i) * ldb + kt * 64);
;     };
;     auto lstore = [&](int s) {
;         char* sb = smem + s * G_STAGE;
; #pragma unroll
;         for (int i = 0; i < 4; ++i) {
;             u32x4 v;
;             if (!AF32) v = ra.v[i];
;             else { const u32x4 a = ra.v[2 * i], b = ra.v[2 * i + 1];
;                 v.x = pk2(__uint_as_float(a.x), __uint_as_float(a.y)); v.y = pk2(__uint_as_float(a.z), __uint_as_float(a.w));
;                 v.z = pk2(__uint_as_float(b.x), __uint_as_float(b.y)); v.w = pk2(__uint_as_float(b.z), __uint_as_float(b.w)); }
;             *(u32x4*)(sb + st_off + i * 8192) = v;
;         }
; #pragma unroll
;         for (int i = 0; i < 2; ++i) *(u32x4*)(sb + G_BOFF + st_off + i * 8192) = rb[i];
;     };
;     __syncthreads();
;     gload(0); lstore(0); __syncthreads();
.LBB0_1905:
	v_lshrrev_b32_e32 v246, 1, v160
	v_lshrrev_b32_e32 v208, 4, v160
	v_bfe_u32 v209, v158, 1, 3
	v_xor_b32_e32 v208, v208, v209
	v_lshlrev_b32_e32 v208, 4, v208
	v_and_b32_e32 v209, 8, v160
	v_lshl_add_u32 v247, v158, 7, v208
	v_add_u32_e32 v247, v247, v209
	v_xor_b32_e32 v248, 64, v247
	v_add_u32_e32 v247, 16, v247
	v_add_u32_e32 v248, 16, v248
	v_add_u32_e32 v250, 0xc000, v247
	v_add_u32_e32 v251, 0xc000, v248
	s_ashr_i32 s0, s42, 31
	s_lshr_b32 s0, s0, 29
	s_add_i32 s1, s42, s0
	s_ashr_i32 s0, s1, 3
	s_lshl_b32 s43, s0, 8
	v_add_u32_e32 v0, s43, v158
	v_min_u32_e32 v1, 0x7fff, v0
	s_and_b32 s1, s1, 0x1fffff8
	v_lshlrev_b32_e32 v1, 8, v1
	v_cmp_lt_i32_e32 vcc, -1, v0
	s_sub_i32 s1, s42, s1
	s_lshl_b32 s28, s1, 7
	v_cndmask_b32_e32 v1, 0, v1, vcc
	v_or_b32_e32 v4, v1, v246
	v_min_i32_e32 v1, 0x7fbf, v0
	v_mov_b32_e32 v2, 0x4000
	s_movk_i32 s1, 0xffbf
	v_lshl_add_u32 v1, v1, 8, v2
	v_cmp_lt_i32_e32 vcc, s1, v0
	v_mov_b32_e32 v2, 0x8000
	s_movk_i32 s1, 0xff7f
	v_cndmask_b32_e32 v1, 0, v1, vcc
	v_or_b32_e32 v176, v1, v246
	v_min_i32_e32 v1, 0x7f7f, v0
	v_lshl_add_u32 v1, v1, 8, v2
	v_cmp_lt_i32_e32 vcc, s1, v0
	v_mov_b32_e32 v5, 0xc000
	s_movk_i32 s1, 0xff3f
	v_cndmask_b32_e32 v1, 0, v1, vcc
	v_or_b32_e32 v2, v1, v246
	v_min_i32_e32 v1, 0x7f3f, v0
	v_lshl_add_u32 v1, v1, 8, v5
	v_cmp_lt_i32_e32 vcc, s1, v0
	v_add_u32_e32 v0, s28, v158
	v_mov_b32_e32 v3, v177
	v_cndmask_b32_e32 v5, 0, v1, vcc
	v_ashrrev_i32_e32 v1, 31, v0
	v_lshlrev_b64 v[0:1], 9, v[0:1]
	v_lshl_add_u64 v[0:1], v[144:145], 0, v[0:1]
	s_mov_b32 s1, 0x8000
	v_lshlrev_b32_e32 v62, 2, v4
	v_or_b32_e32 v4, v5, v246
	v_lshl_add_u64 v[8:9], v[176:177], 2, s[26:27]
	v_mov_b32_e32 v5, v177
	v_lshl_add_u64 v[6:7], v[2:3], 2, s[26:27]
	v_add_co_u32_e32 v2, vcc, s1, v0
	s_barrier
	global_load_dwordx4 v[10:13], v[0:1], off
	global_load_dwordx4 v[14:17], v62, s[26:27] offset:128
	global_load_dwordx4 v[18:21], v62, s[26:27]
	global_load_dwordx4 v[22:25], v[8:9], off offset:128
	global_load_dwordx4 v[26:29], v[8:9], off
	v_lshl_add_u64 v[4:5], v[4:5], 2, s[26:27]
	v_addc_co_u32_e32 v3, vcc, 0, v1, vcc
	global_load_dwordx4 v[30:33], v[6:7], off offset:128
	global_load_dwordx4 v[34:37], v[6:7], off
	global_load_dwordx4 v[38:41], v[4:5], off offset:128
	global_load_dwordx4 v[42:45], v[4:5], off
	global_load_dwordx4 v[46:49], v[2:3], off
	global_load_dwordx4 v[226:229], v62, s[26:27] offset:256
	global_load_dwordx4 v[230:233], v62, s[26:27] offset:384
	global_load_dwordx4 v[234:237], v[8:9], off offset:256
	global_load_dwordx4 v[238:241], v[8:9], off offset:384
	global_load_dwordx4 v[242:245], v[6:7], off offset:256
	global_load_dwordx4 v[58:61], v[6:7], off offset:384
	global_load_dwordx4 v[50:53], v[4:5], off offset:256
	global_load_dwordx4 v[54:57], v[4:5], off offset:384
	v_add_u32_e32 v63, v164, v162
	v_add_u32_e32 v132, v164, v165
	v_add_u32_e32 v133, v164, v166
	v_add_u32_e32 v140, v164, v167
	v_add_u32_e32 v147, 0x14000, v161
	v_add_u32_e32 v148, v169, v162
	v_add_u32_e32 v149, v169, v165
	v_add_u32_e32 v150, v169, v166
	v_add_u32_e32 v151, v169, v167
	v_add_u32_e32 v152, 16, v184
	v_readlane_b32 s20, v254, 28
	v_readfirstlane_b32 s1, v152
	s_mov_b32 m0, s1
	v_readlane_b32 s21, v254, 29
	s_mov_b32 s45, 0
	s_mov_b64 s[40:41], 0
	s_mov_b32 s46, 0
	s_waitcnt vmcnt(17)
	ds_write_b128 v161, v[10:13] offset:32768
	s_waitcnt vmcnt(16)
	v_cvt_pk_bf16_f32 v12, v14, v15
	v_cvt_pk_bf16_f32 v13, v16, v17
	s_waitcnt vmcnt(13)
	v_cvt_pk_bf16_f32 v14, v26, v27
	v_cvt_pk_bf16_f32 v15, v28, v29
	v_cvt_pk_bf16_f32 v10, v18, v19
	v_cvt_pk_bf16_f32 v11, v20, v21
	v_cvt_pk_bf16_f32 v16, v22, v23
	v_cvt_pk_bf16_f32 v17, v24, v25
	s_waitcnt vmcnt(11)
	v_cvt_pk_bf16_f32 v18, v34, v35
	v_cvt_pk_bf16_f32 v19, v36, v37
	v_cvt_pk_bf16_f32 v20, v30, v31
	v_cvt_pk_bf16_f32 v21, v32, v33
	s_waitcnt vmcnt(9)
	v_cvt_pk_bf16_f32 v22, v42, v43
	v_cvt_pk_bf16_f32 v23, v44, v45
	v_cvt_pk_bf16_f32 v24, v38, v39
	v_cvt_pk_bf16_f32 v25, v40, v41
	s_waitcnt vmcnt(8)
	ds_write_b128 v161, v[46:49] offset:40960
	ds_write_b64 v247, v[10:11]
	ds_write_b64 v248, v[12:13]
	ds_write_b64 v247, v[14:15] offset:8192
	ds_write_b64 v248, v[16:17] offset:8192
	ds_write_b64 v247, v[18:19] offset:16384
	ds_write_b64 v248, v[20:21] offset:16384
	ds_write_b64 v247, v[22:23] offset:24576
	ds_write_b64 v248, v[24:25] offset:24576
	s_waitcnt lgkmcnt(0)
	s_barrier
; #define MFMA32(a, b, c) __builtin_amdgcn_mfma_f32_32x32x16_bf16((a), (b), (c), 0, 0, 0)
; template <bool AF32, int AMODE, bool SWAP>
; DI void mainloop_rs(f32x16 (&acc)[2][2], const void* Abase, int lda, int arow0, int amax, const bf16_t* Bbase, int ldb, int brow0, int nk, int tid) {
;     ...
;     for (int kt = 0; kt < nk; ++kt) {
;         const bool more = kt + 1 < nk;
;         if (more) gload(kt + 1);
;         const char* sb = smem + (kt & 1) * G_STAGE;
; #pragma unroll
;         for (int ks = 0; ks < 4; ++ks) {
;             const int co = (lk ^ (2 * ks)) << 4;
;             bf16x8 a0 = *(const bf16x8*)(sb + a_off + co), a1 = *(const bf16x8*)(sb + a_off + 4096 + co);
;             bf16x8 b0 = *(const bf16x8*)(sb + b_off + co), b1 = *(const bf16x8*)(sb + b_off + 4096 + co);
;             if (!SWAP) { acc[0][0] = MFMA32(a0, b0, acc[0][0]); acc[0][1] = MFMA32(a0, b1, acc[0][1]); acc[1][0] = MFMA32(a1, b0, acc[1][0]); acc[1][1] = MFMA32(a1, b1, acc[1][1]); }
;             else { acc[0][0] = MFMA32(b0, a0, acc[0][0]); acc[0][1] = MFMA32(b1, a0, acc[0][1]); acc[1][0] = MFMA32(b0, a1, acc[1][0]); acc[1][1] = MFMA32(b1, a1, acc[1][1]); }
;         }
;         if (more) lstore((kt + 1) & 1);
;         __syncthreads();
	ds_read_b128 v[12:15], v63 offset:32768
	v_add_u32_e32 v10, v163, v162
	ds_read_b128 v[16:19], v10
	ds_read_b128 v[20:23], v10 offset:4096
	ds_read_b128 v[24:27], v63 offset:36864
	s_waitcnt lgkmcnt(2)
	v_mfma_f32_32x32x16_bf16 v[112:127], v[12:15], v[16:19], 0
	v_add_u32_e32 v11, v163, v165
	s_waitcnt lgkmcnt(1)
	v_mfma_f32_32x32x16_bf16 v[80:95], v[12:15], v[20:23], 0
	ds_read_b128 v[12:15], v132 offset:32768
	s_waitcnt lgkmcnt(1)
	v_mfma_f32_32x32x16_bf16 v[96:111], v[24:27], v[16:19], 0
	v_mfma_f32_32x32x16_bf16 v[64:79], v[24:27], v[20:23], 0
	ds_read_b128 v[16:19], v11
	ds_read_b128 v[20:23], v11 offset:4096
	ds_read_b128 v[24:27], v132 offset:36864
	s_waitcnt lgkmcnt(2)
	v_mfma_f32_32x32x16_bf16 v[112:127], v[12:15], v[16:19], v[112:127]
	s_waitcnt lgkmcnt(0)
	v_mfma_f32_32x32x16_bf16 v[96:111], v[24:27], v[16:19], v[96:111]
	v_mfma_f32_32x32x16_bf16 v[80:95], v[12:15], v[20:23], v[80:95]
	ds_read_b128 v[14:17], v133 offset:32768
	v_add_u32_e32 v12, v163, v166
	v_add_u32_e32 v13, v163, v167
	v_mfma_f32_32x32x16_bf16 v[64:79], v[24:27], v[20:23], v[64:79]
	ds_read_b128 v[18:21], v12
	ds_read_b128 v[22:25], v12 offset:4096
	ds_read_b128 v[26:29], v133 offset:36864
	s_waitcnt lgkmcnt(2)
	v_mfma_f32_32x32x16_bf16 v[112:127], v[14:17], v[18:21], v[112:127]
	s_waitcnt lgkmcnt(1)
	v_mfma_f32_32x32x16_bf16 v[80:95], v[14:17], v[22:25], v[80:95]
	ds_read_b128 v[14:17], v140 offset:32768
	s_waitcnt lgkmcnt(1)
	v_mfma_f32_32x32x16_bf16 v[96:111], v[26:29], v[18:21], v[96:111]
	v_mfma_f32_32x32x16_bf16 v[64:79], v[26:29], v[22:25], v[64:79]
	ds_read_b128 v[18:21], v13
	ds_read_b128 v[22:25], v13 offset:4096
	ds_read_b128 v[26:29], v140 offset:36864
	s_waitcnt lgkmcnt(2)
	v_mfma_f32_32x32x16_bf16 v[112:127], v[14:17], v[18:21], v[112:127]
	s_waitcnt lgkmcnt(0)
	v_mfma_f32_32x32x16_bf16 v[96:111], v[26:29], v[18:21], v[96:111]
	global_load_dwordx4 v[34:37], v[0:1], off offset:128
	s_waitcnt vmcnt(4)
	v_cvt_pk_bf16_f32 v18, v242, v243
	v_mfma_f32_32x32x16_bf16 v[80:95], v[14:17], v[22:25], v[80:95]
	global_load_dwordx4 v[14:17], v[2:3], off offset:128
	v_cvt_pk_bf16_f32 v19, v244, v245
	s_waitcnt vmcnt(4)
	v_cvt_pk_bf16_f32 v20, v58, v59
	v_cvt_pk_bf16_f32 v21, v60, v61
	v_mfma_f32_32x32x16_bf16 v[64:79], v[26:29], v[22:25], v[64:79]
	v_cvt_pk_bf16_f32 v22, v226, v227
	v_cvt_pk_bf16_f32 v23, v228, v229
	v_cvt_pk_bf16_f32 v24, v230, v231
	v_cvt_pk_bf16_f32 v25, v232, v233
	v_cvt_pk_bf16_f32 v26, v234, v235
	v_cvt_pk_bf16_f32 v27, v236, v237
	v_cvt_pk_bf16_f32 v28, v238, v239
	v_cvt_pk_bf16_f32 v29, v240, v241
	s_waitcnt vmcnt(3)
	v_cvt_pk_bf16_f32 v30, v50, v51
	v_cvt_pk_bf16_f32 v31, v52, v53
	s_waitcnt vmcnt(2)
	v_cvt_pk_bf16_f32 v32, v54, v55
	v_cvt_pk_bf16_f32 v33, v56, v57
	s_waitcnt vmcnt(1)
	ds_write_b128 v147, v[34:37]
	s_waitcnt vmcnt(0)
	ds_write_b128 v147, v[14:17] offset:8192
	ds_write_b64 v247, v[22:23] offset:49152
	ds_write_b64 v248, v[24:25] offset:49152
	ds_write_b64 v247, v[26:27] offset:57344
	ds_write_b64 v248, v[28:29] offset:57344
	ds_write_b64 v250, v[18:19] offset:16384
	ds_write_b64 v251, v[20:21] offset:16384
	ds_write_b64 v250, v[30:31] offset:24576
	ds_write_b64 v251, v[32:33] offset:24576
	s_waitcnt lgkmcnt(0)
	s_barrier
	ds_read_b128 v[14:17], v148 offset:32768
	ds_read_b128 v[18:21], v10 offset:49152
	ds_read_b128 v[22:25], v10 offset:53248
	ds_read_b128 v[26:29], v148 offset:36864
	s_waitcnt lgkmcnt(2)
	v_mfma_f32_32x32x16_bf16 v[112:127], v[14:17], v[18:21], v[112:127]
	s_waitcnt lgkmcnt(1)
	v_mfma_f32_32x32x16_bf16 v[80:95], v[14:17], v[22:25], v[80:95]
	s_waitcnt lgkmcnt(0)
	v_mfma_f32_32x32x16_bf16 v[96:111], v[26:29], v[18:21], v[96:111]
	v_mfma_f32_32x32x16_bf16 v[64:79], v[26:29], v[22:25], v[64:79]
	ds_read_b128 v[14:17], v149 offset:32768
	ds_read_b128 v[18:21], v11 offset:49152
	ds_read_b128 v[22:25], v11 offset:53248
	ds_read_b128 v[26:29], v149 offset:36864
	s_waitcnt lgkmcnt(2)
	v_mfma_f32_32x32x16_bf16 v[112:127], v[14:17], v[18:21], v[112:127]
	s_waitcnt lgkmcnt(1)
	v_mfma_f32_32x32x16_bf16 v[80:95], v[14:17], v[22:25], v[80:95]
	s_waitcnt lgkmcnt(0)
	v_mfma_f32_32x32x16_bf16 v[96:111], v[26:29], v[18:21], v[96:111]
	v_mfma_f32_32x32x16_bf16 v[64:79], v[26:29], v[22:25], v[64:79]
	ds_read_b128 v[14:17], v150 offset:32768
	ds_read_b128 v[18:21], v12 offset:49152
	ds_read_b128 v[22:25], v12 offset:53248
	ds_read_b128 v[26:29], v150 offset:36864
	s_waitcnt lgkmcnt(2)
	v_mfma_f32_32x32x16_bf16 v[112:127], v[14:17], v[18:21], v[112:127]
	s_waitcnt lgkmcnt(1)
	v_mfma_f32_32x32x16_bf16 v[80:95], v[14:17], v[22:25], v[80:95]
	ds_read_b128 v[14:17], v151 offset:32768
	s_waitcnt lgkmcnt(1)
	v_mfma_f32_32x32x16_bf16 v[96:111], v[26:29], v[18:21], v[96:111]
	v_mfma_f32_32x32x16_bf16 v[64:79], v[26:29], v[22:25], v[64:79]
	global_load_dwordx4 v[18:21], v62, s[26:27] offset:512
	global_load_dwordx4 v[22:25], v62, s[26:27] offset:640
	ds_read_b128 v[26:29], v13 offset:49152
	global_load_dwordx4 v[30:33], v[8:9], off offset:640
	global_load_dwordx4 v[34:37], v[8:9], off offset:512
	ds_read_b128 v[38:41], v13 offset:53248
	ds_read_b128 v[42:45], v151 offset:36864
	global_load_dwordx4 v[46:49], v[6:7], off offset:512
	global_load_dwordx4 v[50:53], v[6:7], off offset:640
	global_load_dwordx4 v[54:57], v[4:5], off offset:512
	global_load_dwordx4 v[58:61], v[4:5], off offset:640
	global_load_dwordx4 v[128:131], v[0:1], off offset:256
	s_waitcnt lgkmcnt(2)
	v_mfma_f32_32x32x16_bf16 v[112:127], v[14:17], v[26:29], v[112:127]
	s_waitcnt lgkmcnt(0)
	v_mfma_f32_32x32x16_bf16 v[96:111], v[42:45], v[26:29], v[96:111]
	global_load_dwordx4 v[26:29], v[2:3], off offset:256
	v_mfma_f32_32x32x16_bf16 v[80:95], v[14:17], v[38:41], v[80:95]
	s_waitcnt vmcnt(9)
	v_cvt_pk_bf16_f32 v14, v18, v19
	v_mfma_f32_32x32x16_bf16 v[64:79], v[42:45], v[38:41], v[64:79]
	v_cvt_pk_bf16_f32 v15, v20, v21
	s_waitcnt vmcnt(8)
	v_cvt_pk_bf16_f32 v16, v22, v23
	v_cvt_pk_bf16_f32 v17, v24, v25
	s_waitcnt vmcnt(6)
	v_cvt_pk_bf16_f32 v18, v34, v35
	v_cvt_pk_bf16_f32 v19, v36, v37
	v_cvt_pk_bf16_f32 v20, v30, v31
	v_cvt_pk_bf16_f32 v21, v32, v33
	s_waitcnt vmcnt(5)
	v_cvt_pk_bf16_f32 v22, v46, v47
	v_cvt_pk_bf16_f32 v23, v48, v49
	s_waitcnt vmcnt(4)
	v_cvt_pk_bf16_f32 v24, v50, v51
	v_cvt_pk_bf16_f32 v25, v52, v53
	s_waitcnt vmcnt(3)
	v_cvt_pk_bf16_f32 v30, v54, v55
	v_cvt_pk_bf16_f32 v31, v56, v57
	s_waitcnt vmcnt(2)
	v_cvt_pk_bf16_f32 v32, v58, v59
	v_cvt_pk_bf16_f32 v33, v60, v61
	s_waitcnt vmcnt(1)
	ds_write_b128 v161, v[128:131] offset:32768
	s_waitcnt vmcnt(0)
	ds_write_b128 v161, v[26:29] offset:40960
	ds_write_b64 v247, v[14:15]
	ds_write_b64 v248, v[16:17]
	ds_write_b64 v247, v[18:19] offset:8192
	ds_write_b64 v248, v[20:21] offset:8192
	ds_write_b64 v247, v[22:23] offset:16384
	ds_write_b64 v248, v[24:25] offset:16384
	ds_write_b64 v247, v[30:31] offset:24576
	ds_write_b64 v248, v[32:33] offset:24576
	s_waitcnt lgkmcnt(0)
	s_barrier
; template <bool AF32, int AMODE, bool SWAP>
; DI void mainloop_rs(f32x16 (&acc)[2][2], const void* Abase, int lda, int arow0, int amax, const bf16_t* Bbase, int ldb, int brow0, int nk, int tid) {
;     ...
;     auto gload = [&](int kt) {
;         const int ka = (AMODE == 1) ? ((kt >> 1) * 192 + (kt & 1) * 64) : kt * 64;
; #pragma unroll
;         for (int i = 0; i < 4; ++i) {
;             if (!AF32) ra.v[i] = *(const u32x4*)((const bf16_t*)Abase + arow[i] + ka);
;             else { const float* p = (const float*)Abase + arow[i] + ka; ra.v[2 * i] = *(const u32x4*)p; ra.v[2 * i + 1] = *(const u32x4*)(p + 4); }
;         }
; #pragma unroll
;         for (int i = 0; i < 2; ++i) rb[i] = *(const u32x4*)(bp + (long)(64 * i) * ldb + kt * 64);
;     };
;     auto lstore = [&](int s) {
;         char* sb = smem + s * G_STAGE;
; #pragma unroll
;         for (int i = 0; i < 4; ++i) {
;             u32x4 v;
;             if (!AF32) v = ra.v[i];
;             else { const u32x4 a = ra.v[2 * i], b = ra.v[2 * i + 1];
;                 v.x = pk2(__uint_as_float(a.x), __uint_as_float(a.y)); v.y = pk2(__uint_as_float(a.z), __uint_as_float(a.w));
;                 v.z = pk2(__uint_as_float(b.x), __uint_as_float(b.y)); v.w = pk2(__uint_as_float(b.z), __uint_as_float(b.w)); }
;             *(u32x4*)(sb + st_off + i * 8192) = v;
;         }
; #pragma unroll
;         for (int i = 0; i < 2; ++i) *(u32x4*)(sb + G_BOFF + st_off + i * 8192) = rb[i];
;     };
;     __syncthreads();
;     gload(0); lstore(0); __syncthreads();
;     for (int kt = 0; kt < nk; ++kt) {
;         const bool more = kt + 1 < nk;
;         if (more) gload(kt + 1);
;         const char* sb = smem + (kt & 1) * G_STAGE;
; #pragma unroll
;         for (int ks = 0; ks < 4; ++ks) {
;             const int co = (lk ^ (2 * ks)) << 4;
;             bf16x8 a0 = *(const bf16x8*)(sb + a_off + co), a1 = *(const bf16x8*)(sb + a_off + 4096 + co);
;             bf16x8 b0 = *(const bf16x8*)(sb + b_off + co), b1 = *(const bf16x8*)(sb + b_off + 4096 + co);
;             if (!SWAP) { acc[0][0] = MFMA32(a0, b0, acc[0][0]); acc[0][1] = MFMA32(a0, b1, acc[0][1]); acc[1][0] = MFMA32(a1, b0, acc[1][0]); acc[1][1] = MFMA32(a1, b1, acc[1][1]); }
;             else { acc[0][0] = MFMA32(b0, a0, acc[0][0]); acc[0][1] = MFMA32(b1, a0, acc[0][1]); acc[1][0] = MFMA32(b0, a1, acc[1][0]); acc[1][1] = MFMA32(b1, a1, acc[1][1]); }
;         }
	ds_read_b128 v[14:17], v63 offset:32768
	ds_read_b128 v[18:21], v10
	ds_read_b128 v[22:25], v10 offset:4096
	ds_read_b128 v[26:29], v63 offset:36864
	s_waitcnt lgkmcnt(2)
	v_mfma_f32_32x32x16_bf16 v[112:127], v[14:17], v[18:21], v[112:127]
	v_lshlrev_b32_e32 v63, 1, v174
	s_waitcnt lgkmcnt(0)
	v_mfma_f32_32x32x16_bf16 v[96:111], v[26:29], v[18:21], v[96:111]
	v_mfma_f32_32x32x16_bf16 v[80:95], v[14:17], v[22:25], v[80:95]
	global_load_dwordx4 v[14:17], v62, s[26:27] offset:768
	global_load_dwordx4 v[18:21], v62, s[26:27] offset:896
	global_load_dwordx4 v[30:33], v[8:9], off offset:768
	global_load_dwordx4 v[34:37], v[8:9], off offset:896
	ds_read_b128 v[38:41], v132 offset:32768
	s_waitcnt vmcnt(3)
	v_cvt_pk_bf16_f32 v14, v14, v15
	v_mfma_f32_32x32x16_bf16 v[64:79], v[26:29], v[22:25], v[64:79]
	global_load_dwordx4 v[22:25], v[6:7], off offset:768
	s_nop 0
	global_load_dwordx4 v[6:9], v[6:7], off offset:896
	ds_read_b128 v[26:29], v11
	global_load_dwordx4 v[42:45], v[4:5], off offset:896
	global_load_dwordx4 v[46:49], v[4:5], off offset:768
	global_load_dwordx4 v[50:53], v[0:1], off offset:384
	ds_read_b128 v[54:57], v11 offset:4096
	ds_read_b128 v[58:61], v132 offset:36864
	global_load_dwordx4 v[0:3], v[2:3], off offset:384
	v_add_u32_e32 v4, s43, v173
	v_add_u32_e32 v5, s43, v175
	s_waitcnt lgkmcnt(2)
	v_mfma_f32_32x32x16_bf16 v[112:127], v[38:41], v[26:29], v[112:127]
	v_med3_i32 v4, v4, 0, v211
	v_med3_i32 v153, v5, 0, v211
	v_add_u32_e32 v5, s28, v181
	v_lshl_or_b32 v62, v5, 10, v174
	v_lshl_or_b32 v154, v4, 11, v63
	v_cvt_pk_bf16_f32 v15, v16, v17
	s_waitcnt vmcnt(8)
	v_cvt_pk_bf16_f32 v16, v18, v19
	s_waitcnt lgkmcnt(0)
	v_mfma_f32_32x32x16_bf16 v[96:111], v[58:61], v[26:29], v[96:111]
	v_add_u32_e32 v26, s43, v179
	v_add_u32_e32 v27, s43, v180
	v_med3_i32 v155, v26, 0, v211
	v_add_u32_e32 v26, s28, v182
	v_med3_i32 v156, v27, 0, v211
	v_lshl_or_b32 v146, v26, 10, v178
	ds_read_b128 v[26:29], v133 offset:32768
	v_mfma_f32_32x32x16_bf16 v[80:95], v[38:41], v[54:57], v[80:95]
	v_cvt_pk_bf16_f32 v17, v20, v21
	s_waitcnt vmcnt(7)
	v_cvt_pk_bf16_f32 v18, v30, v31
	v_cvt_pk_bf16_f32 v19, v32, v33
	s_waitcnt vmcnt(6)
	v_cvt_pk_bf16_f32 v20, v34, v35
	v_cvt_pk_bf16_f32 v21, v36, v37
	v_lshl_or_b32 v176, v155, 11, v63
	v_ashrrev_i32_e32 v63, 31, v62
	v_mfma_f32_32x32x16_bf16 v[64:79], v[58:61], v[54:57], v[64:79]
	ds_read_b128 v[38:41], v12
	ds_read_b128 v[54:57], v12 offset:4096
	ds_read_b128 v[58:61], v133 offset:36864
	ds_read_b128 v[128:131], v13
	ds_read_b128 v[132:135], v13 offset:4096
	ds_read_b128 v[136:139], v140 offset:32768
	ds_read_b128 v[140:143], v140 offset:36864
	s_waitcnt vmcnt(1)
	ds_write_b128 v147, v[50:53]
	s_waitcnt vmcnt(0)
	ds_write_b128 v147, v[0:3] offset:8192
	s_waitcnt lgkmcnt(8)
	v_mfma_f32_32x32x16_bf16 v[112:127], v[26:29], v[38:41], v[112:127]
	v_cvt_pk_bf16_f32 v4, v22, v23
	v_cvt_pk_bf16_f32 v5, v24, v25
	v_cvt_pk_bf16_f32 v6, v6, v7
	v_cvt_pk_bf16_f32 v7, v8, v9
	v_cvt_pk_bf16_f32 v22, v46, v47
	v_cvt_pk_bf16_f32 v23, v48, v49
	v_cvt_pk_bf16_f32 v24, v42, v43
	s_waitcnt lgkmcnt(6)
	v_mfma_f32_32x32x16_bf16 v[96:111], v[58:61], v[38:41], v[96:111]
	v_cvt_pk_bf16_f32 v25, v44, v45
	ds_write_b64 v247, v[14:15] offset:49152
	ds_write_b64 v248, v[16:17] offset:49152
	ds_write_b64 v247, v[18:19] offset:57344
	ds_write_b64 v248, v[20:21] offset:57344
	ds_write_b64 v250, v[4:5] offset:16384
	ds_write_b64 v251, v[6:7] offset:16384
	ds_write_b64 v250, v[22:23] offset:24576
	ds_write_b64 v251, v[24:25] offset:24576
	s_waitcnt lgkmcnt(0)
	s_barrier
	ds_read_b128 v[0:3], v10 offset:49152
	ds_read_b128 v[4:7], v10 offset:53248
	ds_read_b128 v[14:17], v148 offset:32768
	ds_read_b128 v[18:21], v148 offset:36864
	ds_read_b128 v[22:25], v11 offset:49152
	ds_read_b128 v[8:11], v11 offset:53248
	ds_read_b128 v[30:33], v149 offset:32768
	ds_read_b128 v[34:37], v149 offset:36864
	ds_read_b128 v[38:41], v12 offset:49152
	ds_read_b128 v[48:51], v12 offset:53248
	ds_read_b128 v[44:47], v150 offset:32768
	ds_read_b128 v[192:195], v150 offset:36864
	ds_read_b128 v[196:199], v13 offset:49152
	ds_read_b128 v[200:203], v13 offset:53248
	ds_read_b128 v[204:207], v151 offset:32768
	ds_read_b128 v[222:225], v151 offset:36864
	v_lshlrev_b32_e32 v13, 1, v178
	v_mfma_f32_32x32x16_bf16 v[80:95], v[26:29], v[54:57], v[80:95]
	v_add_u32_e32 v26, 0x400, v152
	s_waitcnt lgkmcnt(0)
	v_readfirstlane_b32 s1, v26
	v_add_u32_e32 v26, 0x800, v152
	s_barrier
	s_waitcnt lgkmcnt(0)
	v_mfma_f32_32x32x16_bf16 v[112:127], v[136:139], v[128:131], v[112:127]
	s_barrier
; #define MFMA32(a, b, c) __builtin_amdgcn_mfma_f32_32x32x16_bf16((a), (b), (c), 0, 0, 0)
; #define RAW_BARRIER() do { asm volatile("s_waitcnt lgkmcnt(0)" ::: "memory"); __builtin_amdgcn_s_barrier(); } while (0)
; template <bool AF32, int AMODE, bool SWAP>
; DI void mainloop_rs(f32x16 (&acc)[2][2], const void* Abase, int lda, int arow0, int amax, const bf16_t* Bbase, int ldb, int brow0, int nk, int tid) {
;     ...
; #pragma unroll
;         for (int ks = 0; ks < 4; ++ks) {
;             const int co = (lk ^ (2 * ks)) << 4;
;             bf16x8 a0 = *(const bf16x8*)(sb + a_off + co), a1 = *(const bf16x8*)(sb + a_off + 4096 + co);
;             bf16x8 b0 = *(const bf16x8*)(sb + b_off + co), b1 = *(const bf16x8*)(sb + b_off + 4096 + co);
;             if (!SWAP) { acc[0][0] = MFMA32(a0, b0, acc[0][0]); acc[0][1] = MFMA32(a0, b1, acc[0][1]); acc[1][0] = MFMA32(a1, b0, acc[1][0]); acc[1][1] = MFMA32(a1, b1, acc[1][1]); }
;             else { acc[0][0] = MFMA32(b0, a0, acc[0][0]); acc[0][1] = MFMA32(b1, a0, acc[0][1]); acc[1][0] = MFMA32(b0, a1, acc[1][0]); acc[1][1] = MFMA32(b1, a1, acc[1][1]); }
;         }
; template <int AMODE, bool SWAP, int MI>
; DI void mainloop_dma(f32x16 (&acc)[MI][2], const TD& c, const TD& n, bool hasn, bool primed, int& s, int tid) {
;     ...
;     offs(c, ao, bo);
;     const int nk = c.nk;
;     if (!primed) {
;         RAW_BARRIER();
;         s = 0;
; #pragma unroll
;         for (int i = 0; i < NP; ++i) piece(c, ao, bo, 0, 0, i);
;         if (MI == 2 && nk > 1) {
; #pragma unroll
;             for (int i = 0; i < NP; ++i) piece(c, ao, bo, 1, 1, i);
;         }
;     }
	global_load_lds_dwordx4 v154, s[20:21]
	v_lshl_or_b32 v12, v153, 11, v13
	s_mov_b32 m0, s1
	v_readfirstlane_b32 s1, v26
	v_lshl_or_b32 v26, v156, 11, v13
	v_mfma_f32_32x32x16_bf16 v[96:111], v[140:143], v[128:131], v[96:111]
	v_add_u32_e32 v13, 0xc00, v152
	global_load_lds_dwordx4 v12, s[20:21]
	s_mov_b32 m0, s1
	v_readfirstlane_b32 s1, v13
	v_add_u32_e32 v13, 16, v183
	v_add_u32_e32 v27, 0x8000, v13
	global_load_lds_dwordx4 v176, s[20:21]
	s_mov_b32 m0, s1
	v_readfirstlane_b32 s1, v27
	v_add_u32_e32 v13, 0x8400, v13
	global_load_lds_dwordx4 v26, s[20:21]
	v_lshl_add_u64 v[28:29], v[62:63], 1, s[18:19]
	s_mov_b32 m0, s1
	v_ashrrev_i32_e32 v147, 31, v146
	v_readfirstlane_b32 s1, v13
	v_add_u32_e32 v13, 0xc000, v152
	global_load_lds_dwordx4 v[28:29], off
	v_lshl_add_u64 v[42:43], v[146:147], 1, s[18:19]
	s_mov_b32 m0, s1
	v_readfirstlane_b32 s1, v13
	v_readlane_b32 s20, v254, 52
	v_add_u32_e32 v13, 0xc400, v152
	global_load_lds_dwordx4 v[42:43], off
	s_mov_b32 m0, s1
	v_readlane_b32 s21, v254, 53
	v_readfirstlane_b32 s1, v13
	v_add_u32_e32 v13, 0xc800, v152
	v_mfma_f32_32x32x16_bf16 v[112:127], v[14:17], v[0:3], v[112:127]
	v_mov_b32_e32 v27, v177
	v_mov_b32_e32 v155, v177
	global_load_lds_dwordx4 v154, s[20:21]
	s_mov_b32 m0, s1
	v_readfirstlane_b32 s1, v13
	v_add_u32_e32 v13, 0xcc00, v152
	v_mfma_f32_32x32x16_bf16 v[96:111], v[18:21], v[0:3], v[96:111]
	v_add_u32_e32 v2, s52, v183
	global_load_lds_dwordx4 v12, s[20:21]
	s_mov_b32 m0, s1
	v_readfirstlane_b32 s1, v13
	v_add_u32_e32 v3, 0x1000, v2
	global_load_lds_dwordx4 v176, s[20:21]
	s_mov_b32 m0, s1
	v_readfirstlane_b32 s1, v3
	v_add_u32_e32 v2, 0x1400, v2
	global_load_lds_dwordx4 v26, s[20:21]
	v_lshl_add_u64 v[0:1], v[28:29], 0, s[94:95]
	s_mov_b32 m0, s1
	v_readfirstlane_b32 s1, v2
	global_load_lds_dwordx4 v[0:1], off
	v_lshl_add_u64 v[0:1], v[42:43], 0, s[94:95]
	s_mov_b32 m0, s1
	v_mfma_f32_32x32x16_bf16 v[64:79], v[58:61], v[54:57], v[64:79]
	global_load_lds_dwordx4 v[0:1], off
	v_lshl_add_u32 v0, s42, 17, v190
	s_lshl_b32 s1, s0, 20
	v_subrev_u32_e32 v0, s1, v0
	v_ashrrev_i32_e32 v1, 31, v0
	v_lshl_add_u64 v[146:147], v[0:1], 1, s[48:49]
	v_mfma_f32_32x32x16_bf16 v[80:95], v[136:139], v[132:135], v[80:95]
	v_lshl_add_u32 v0, s42, 7, v181
	s_lshl_b32 s0, s0, 10
	v_subrev_u32_e32 v0, s0, v0
	v_lshl_or_b32 v0, v0, 10, v174
	v_ashrrev_i32_e32 v1, 31, v0
	v_lshl_add_u64 v[148:149], v[0:1], 1, s[48:49]
	v_mov_b32_e32 v13, v177
	v_mfma_f32_32x32x16_bf16 v[64:79], v[140:143], v[132:135], v[64:79]
	v_mov_b32_e32 v0, 0
	v_lshl_add_u64 v[150:151], s[50:51], 0, v[176:177]
	v_lshl_add_u64 v[152:153], s[50:51], 0, v[26:27]
	v_lshl_add_u64 v[154:155], s[50:51], 0, v[154:155]
	v_lshl_add_u64 v[156:157], s[50:51], 0, v[12:13]
	v_mov_b32_e32 v1, v0
	v_mov_b32_e32 v2, v0
	v_mfma_f32_32x32x16_bf16 v[80:95], v[14:17], v[4:7], v[80:95]
	v_mov_b32_e32 v3, v0
	v_mov_b32_e32 v12, v0
	v_mov_b32_e32 v13, v0
	v_mov_b32_e32 v14, v0
	v_mov_b32_e32 v15, v0
	v_mov_b32_e32 v42, v0
	v_mov_b32_e32 v43, v0
	v_mfma_f32_32x32x16_bf16 v[64:79], v[18:21], v[4:7], v[64:79]
	v_mov_b32_e32 v4, v0
	v_mov_b32_e32 v5, v0
	v_mov_b32_e32 v6, v0
	v_mov_b32_e32 v7, v0
	v_mov_b32_e32 v16, v0
	v_mov_b32_e32 v17, v0
	v_mov_b32_e32 v18, v0
	v_mfma_f32_32x32x16_bf16 v[112:127], v[30:33], v[22:25], v[112:127]
	v_mov_b32_e32 v19, v0
	v_mov_b32_e32 v20, v0
	v_mov_b32_e32 v21, v0
	v_mov_b32_e32 v26, v0
	v_mov_b32_e32 v27, v0
	v_mov_b32_e32 v28, v0
	v_mov_b32_e32 v29, v0
	v_mfma_f32_32x32x16_bf16 v[96:111], v[34:37], v[22:25], v[96:111]
	v_mov_b32_e32 v22, v0
	v_mov_b32_e32 v23, v0
	v_mov_b32_e32 v24, v0
	v_mov_b32_e32 v25, v0
	v_mov_b32_e32 v52, v0
	v_mov_b32_e32 v53, v0
	v_mov_b32_e32 v54, v0
	v_mfma_f32_32x32x16_bf16 v[80:95], v[30:33], v[8:11], v[80:95]
	v_mov_b32_e32 v32, v0
	v_mov_b32_e32 v33, v0
	v_mov_b32_e32 v30, v0
	v_mov_b32_e32 v31, v0
	v_mov_b32_e32 v55, v0
	v_mov_b32_e32 v56, v0
	v_mov_b32_e32 v57, v0
	v_mfma_f32_32x32x16_bf16 v[64:79], v[34:37], v[8:11], v[64:79]
	v_mov_b32_e32 v8, v0
	v_mov_b32_e32 v9, v0
	v_mov_b32_e32 v10, v0
	v_mov_b32_e32 v11, v0
	v_mov_b32_e32 v34, v0
	v_mov_b32_e32 v35, v0
	v_mov_b32_e32 v36, v0
	v_mfma_f32_32x32x16_bf16 v[112:127], v[44:47], v[38:41], v[112:127]
	v_mov_b32_e32 v37, v0
	v_mov_b32_e32 v58, v0
	v_mov_b32_e32 v59, v0
	v_mov_b32_e32 v60, v0
	v_mov_b32_e32 v61, v0
	v_mov_b32_e32 v62, v0
	v_mov_b32_e32 v63, v0
	v_mfma_f32_32x32x16_bf16 v[96:111], v[192:195], v[38:41], v[96:111]
	v_mov_b32_e32 v38, v0
	v_mov_b32_e32 v39, v0
	v_mov_b32_e32 v40, v0
	v_mov_b32_e32 v41, v0
	v_mfma_f32_32x32x16_bf16 v[80:95], v[44:47], v[48:51], v[80:95]
	v_mov_b32_e32 v44, v0
	v_mov_b32_e32 v45, v0
	v_mov_b32_e32 v46, v0
	v_mov_b32_e32 v47, v0
	v_mfma_f32_32x32x16_bf16 v[64:79], v[192:195], v[48:51], v[64:79]
	v_mov_b32_e32 v48, v0
	v_mov_b32_e32 v49, v0
	v_mov_b32_e32 v50, v0
	v_mov_b32_e32 v51, v0
	v_mfma_f32_32x32x16_bf16 v[112:127], v[204:207], v[196:199], v[112:127]
	v_mfma_f32_32x32x16_bf16 v[96:111], v[222:225], v[196:199], v[96:111]
	v_mfma_f32_32x32x16_bf16 v[80:95], v[204:207], v[200:203], v[80:95]
	v_mfma_f32_32x32x16_bf16 v[64:79], v[222:225], v[200:203], v[64:79]
	s_branch .LBB0_1907
